# dt_units K loop: 26 fragment loads issued up front plus 6 refills, counted vmcnt instead of six full drains
# speedup vs baseline: 1.0070x; 1.0070x over previous
; #define LAS __attribute__((address_space(3)))
; #define LBAR() do { asm volatile("s_waitcnt lgkmcnt(0)" ::: "memory"); __builtin_amdgcn_s_barrier(); asm volatile("" ::: "memory"); } while (0)
; #define MFMA16(a, b, c) __builtin_amdgcn_mfma_f32_16x16x32_bf16((a), (b), (c), 0, 0, 0)
; __device__ __forceinline__ void dt_units(LAS unsigned char* lds, const bf16_t* xb, const bf16_t* WinT, const float* stat, const float* c1, const float* c2, float* dtbuf, int fold, bf16_t* proj, const int ufirst, const int ustride, const int uend) {
;     ...
;         const bf16_t* ap = xb + (size_t)(u * 64 + rb4 * 16 + fr) * 1024 + kh * 512 + fq * 8;
;         const bf16_t* bp = WinT + (size_t)(NPROJ + fr) * 1024 + kh * 512 + fq * 8;
;         f32x4 acc = (f32x4){0.f, 0.f, 0.f, 0.f};
;         { bf16x8 af[16], bf[16];
; #pragma unroll
;             for (int s = 0; s < 16; ++s) { af[s] = *(const bf16x8*)(ap + s * 32); bf[s] = *(const bf16x8*)(bp + s * 32); }
; #pragma unroll
;             for (int s = 0; s < 16; ++s) acc = MFMA16(bf[s], af[s], acc);
;         }
;         *(LAS f32x4*)(red + (kh * 64 + rb4 * 16 + fr) * 20 + fq * 4) = acc;
;         LBAR();
;         if (tid < 128) {
;             const int r = tid >> 1, c4 = (tid & 1) * 4; const int row = u * 64 + r;
;             f32x4 v = *(const LAS f32x4*)(red + r * 20 + c4) + *(const LAS f32x4*)(red + (64 + r) * 20 + c4);
;             if (fold) {
;                 const f32x4* sp = (const f32x4*)(stat + (size_t)row * 32); float s1 = 0.f, s2 = 0.f;
; #pragma unroll
;                 for (int q = 0; q < 8; ++q) { const f32x4 t = sp[q]; s1 += t[0] + t[2]; s2 += t[1] + t[3]; }
;                 const float mu = s1 * (1.0f / 1024.0f), var = fmaxf(s2 * (1.0f / 1024.0f) - mu * mu, 0.f), rstd = __builtin_amdgcn_rsqf(var + LN_EPS);
;                 const f32x4 k1 = *(const f32x4*)(c1 + NPROJ + c4), k2 = *(const f32x4*)(c2 + NPROJ + c4); v = (v - k1 * mu) * rstd + k2;
.LBB0_921:
	s_or_b64 exec, exec, s[20:21]
	s_lshl_b32 s14, s18, 6
	v_or_b32_e32 v18, s14, v23
	v_ashrrev_i32_e32 v19, 31, v18
	v_lshlrev_b64 v[18:19], 11, v[18:19]
	v_lshl_add_u64 v[64:65], v[2:3], 0, v[18:19]
	global_load_dwordx4 v[18:21], v[12:13], off
	global_load_dwordx4 v[28:31], v[64:65], off
	global_load_dwordx4 v[32:35], v[12:13], off offset:64
	global_load_dwordx4 v[36:39], v[64:65], off offset:64
	global_load_dwordx4 v[40:43], v[12:13], off offset:128
	global_load_dwordx4 v[44:47], v[64:65], off offset:128
	global_load_dwordx4 v[48:51], v[12:13], off offset:192
	global_load_dwordx4 v[52:55], v[64:65], off offset:192
	global_load_dwordx4 v[56:59], v[12:13], off offset:256
	global_load_dwordx4 v[60:63], v[64:65], off offset:256
	global_load_dwordx4 v[88:91], v[12:13], off offset:320
	global_load_dwordx4 v[102:105], v[64:65], off offset:320
	global_load_dwordx4 v[120:123], v[12:13], off offset:384
	global_load_dwordx4 v[138:141], v[64:65], off offset:384
	global_load_dwordx4 v[148:151], v[12:13], off offset:448
	global_load_dwordx4 v[152:155], v[64:65], off offset:448
	global_load_dwordx4 v[160:163], v[12:13], off offset:512
	global_load_dwordx4 v[164:167], v[64:65], off offset:512
	global_load_dwordx4 v[184:187], v[12:13], off offset:576
	global_load_dwordx4 v[188:191], v[64:65], off offset:576
	global_load_dwordx4 v[222:225], v[12:13], off offset:640
	global_load_dwordx4 v[226:229], v[64:65], off offset:640
	global_load_dwordx4 v[230:233], v[12:13], off offset:704
	global_load_dwordx4 v[234:237], v[64:65], off offset:704
	global_load_dwordx4 v[238:241], v[12:13], off offset:768
	global_load_dwordx4 v[242:245], v[64:65], off offset:768
	s_waitcnt vmcnt(24)
	v_mfma_f32_16x16x32_bf16 v[8:11], v[18:21], v[28:31], 0
	global_load_dwordx4 v[18:21], v[12:13], off offset:832
	global_load_dwordx4 v[28:31], v[64:65], off offset:832
	s_waitcnt vmcnt(24)
	v_mfma_f32_16x16x32_bf16 v[8:11], v[32:35], v[36:39], v[8:11]
	global_load_dwordx4 v[32:35], v[12:13], off offset:896
	global_load_dwordx4 v[36:39], v[64:65], off offset:896
	s_waitcnt vmcnt(24)
	v_mfma_f32_16x16x32_bf16 v[8:11], v[40:43], v[44:47], v[8:11]
	global_load_dwordx4 v[40:43], v[12:13], off offset:960
	global_load_dwordx4 v[44:47], v[64:65], off offset:960
	s_waitcnt vmcnt(24)
	v_mfma_f32_16x16x32_bf16 v[8:11], v[48:51], v[52:55], v[8:11]
	s_waitcnt vmcnt(22)
	v_mfma_f32_16x16x32_bf16 v[8:11], v[56:59], v[60:63], v[8:11]
	s_waitcnt vmcnt(20)
	v_mfma_f32_16x16x32_bf16 v[8:11], v[88:91], v[102:105], v[8:11]
	s_waitcnt vmcnt(18)
	v_mfma_f32_16x16x32_bf16 v[8:11], v[120:123], v[138:141], v[8:11]
	s_waitcnt vmcnt(16)
	v_mfma_f32_16x16x32_bf16 v[8:11], v[148:151], v[152:155], v[8:11]
	s_waitcnt vmcnt(14)
	v_mfma_f32_16x16x32_bf16 v[8:11], v[160:163], v[164:167], v[8:11]
	s_waitcnt vmcnt(12)
	v_mfma_f32_16x16x32_bf16 v[8:11], v[184:187], v[188:191], v[8:11]
	s_waitcnt vmcnt(10)
	v_mfma_f32_16x16x32_bf16 v[8:11], v[222:225], v[226:229], v[8:11]
	s_waitcnt vmcnt(8)
	v_mfma_f32_16x16x32_bf16 v[8:11], v[230:233], v[234:237], v[8:11]
	s_waitcnt vmcnt(6)
	v_mfma_f32_16x16x32_bf16 v[8:11], v[238:241], v[242:245], v[8:11]
	s_waitcnt vmcnt(4)
	v_mfma_f32_16x16x32_bf16 v[8:11], v[18:21], v[28:31], v[8:11]
	s_waitcnt vmcnt(2)
	v_mfma_f32_16x16x32_bf16 v[8:11], v[32:35], v[36:39], v[8:11]
	s_waitcnt vmcnt(0)
	v_mfma_f32_16x16x32_bf16 v[8:11], v[40:43], v[44:47], v[8:11]
	s_nop 7
	ds_write_b128 v26, v[8:11]
	s_waitcnt lgkmcnt(0)
	s_barrier
	s_and_saveexec_b64 s[20:21], s[42:43]
	s_cbranch_execz .LBB0_917
	ds_read_b128 v[28:31], v25
	ds_read_b128 v[32:35], v25 offset:5120
	v_add_u32_e32 v18, s14, v24
	s_and_b64 vcc, exec, s[40:41]
	v_ashrrev_i32_e32 v19, 31, v18
	s_waitcnt lgkmcnt(0)
	v_pk_add_f32 v[8:9], v[30:31], v[34:35]
	v_pk_add_f32 v[20:21], v[28:29], v[32:33]
	s_cbranch_vccnz .LBB0_924
	v_lshlrev_b64 v[10:11], 7, v[18:19]
	v_lshl_add_u64 v[10:11], s[34:35], 0, v[10:11]
	global_load_dwordx4 v[28:31], v[10:11], off offset:48
	global_load_dwordx4 v[32:35], v[10:11], off offset:32
	global_load_dwordx4 v[36:39], v[10:11], off offset:16
	global_load_dwordx4 v[40:43], v[10:11], off
	global_load_dwordx4 v[44:47], v[10:11], off offset:112
	global_load_dwordx4 v[48:51], v[10:11], off offset:96
	global_load_dwordx4 v[52:55], v[10:11], off offset:80
	global_load_dwordx4 v[56:59], v[10:11], off offset:64
	s_waitcnt vmcnt(7)
	v_pk_add_f32 v[28:29], v[28:29], v[30:31]
	s_waitcnt vmcnt(6)
	v_pk_add_f32 v[32:33], v[32:33], v[34:35]
	s_waitcnt vmcnt(5)
	v_pk_add_f32 v[36:37], v[36:37], v[38:39]
	s_waitcnt vmcnt(4)
	v_pk_add_f32 v[10:11], v[40:41], v[42:43]
	s_nop 0
	v_pk_add_f32 v[10:11], v[10:11], 0 op_sel_hi:[1,0]
	s_nop 0
	v_pk_add_f32 v[10:11], v[10:11], v[36:37]
	s_nop 0
	v_pk_add_f32 v[10:11], v[10:11], v[32:33]
	s_nop 0
	v_pk_add_f32 v[10:11], v[10:11], v[28:29]
	s_waitcnt vmcnt(0)
	v_pk_add_f32 v[28:29], v[56:57], v[58:59]
	s_nop 0
	v_pk_add_f32 v[10:11], v[10:11], v[28:29]
	v_pk_add_f32 v[28:29], v[52:53], v[54:55]
	s_nop 0
	v_pk_add_f32 v[10:11], v[10:11], v[28:29]
	v_pk_add_f32 v[28:29], v[48:49], v[50:51]
	s_nop 0
	v_pk_add_f32 v[10:11], v[10:11], v[28:29]
	v_pk_add_f32 v[28:29], v[44:45], v[46:47]
	s_nop 0
	v_pk_add_f32 v[10:11], v[10:11], v[28:29]
	global_load_dwordx4 v[28:31], v[14:15], off
	global_load_dwordx4 v[32:35], v[16:17], off
	v_pk_mul_f32 v[10:11], v[10:11], s[0:1] op_sel_hi:[1,0]
	s_nop 0
	v_fma_f32 v0, -v10, v10, v11
	v_max_f32_e32 v0, 0, v0
	v_add_f32_e32 v0, 0x3727c5ac, v0
	v_rsq_f32_e32 v0, v0
	s_waitcnt vmcnt(1)
	v_pk_fma_f32 v[20:21], v[28:29], v[10:11], v[20:21] op_sel_hi:[1,0,1] neg_lo:[1,0,0] neg_hi:[1,0,0]
	v_xor_b32_e32 v29, 0x80000000, v31
	v_xor_b32_e32 v28, 0x80000000, v30
	v_pk_fma_f32 v[8:9], v[28:29], v[10:11], v[8:9] op_sel_hi:[1,0,1]
	s_waitcnt vmcnt(0)
	v_pk_fma_f32 v[20:21], v[20:21], v[0:1], v[32:33] op_sel_hi:[1,0,1]
	v_pk_fma_f32 v[8:9], v[8:9], v[0:1], v[34:35] op_sel_hi:[1,0,1]
